# P4 bias item (pe@W1): serial 1024-iteration load-wait-fma loop rewritten with 40 loads in flight per round + lane reduction
# speedup vs baseline: 1.0726x; 1.0726x over previous
.LBB0_140:
	s_cmpk_gt_u32 s44, 0x12bf
	s_cbranch_scc0 .LBB0_168
	s_cmpk_gt_u32 s44, 0x13bf
	s_cbranch_scc0 .LBB0_165
	s_cmpk_gt_u32 s44, 0x147f
	s_cbranch_scc0 .LBB0_162
	s_cmpk_gt_u32 s44, 0x167f
	s_cbranch_scc0 .LBB0_159
	s_cmpk_gt_u32 s44, 0x177f
	s_cbranch_scc0 .LBB0_156
	s_cmpk_gt_u32 s44, 0x1787
	s_cbranch_scc0 .LBB0_153
	s_add_i32 s22, s44, 0xffffe878
	s_lshl_b32 s20, s7, 2
	s_and_b32 s23, s20, 0x180
	s_cmp_lt_u32 s22, 4
	v_readlane_b32 s52, v254, 42
	v_readlane_b32 s53, v254, 43
	v_readlane_b32 s58, v254, 48
	v_readlane_b32 s59, v254, 49
	s_cselect_b32 s25, s36, s38
	s_cselect_b32 s24, s35, s37
	s_cselect_b32 s21, s53, s59
	s_cselect_b32 s20, s52, s58
	v_readlane_b32 s54, v254, 44
	v_readlane_b32 s55, v254, 45
	v_readlane_b32 s56, v254, 46
	v_readlane_b32 s57, v254, 47
	v_readlane_b32 s60, v254, 50
	v_readlane_b32 s61, v254, 51
	v_readlane_b32 s62, v254, 52
	v_readlane_b32 s63, v254, 53
	v_readlane_b32 s64, v254, 54
	v_readlane_b32 s65, v254, 55
	v_readlane_b32 s66, v254, 56
	v_readlane_b32 s67, v254, 57
	v_mbcnt_lo_u32_b32 v54, -1, 0
	v_mbcnt_hi_u32_b32 v54, -1, v54
	v_and_b32_e32 v55, 7, v54
	v_lshrrev_b32_e32 v60, 3, v54
	v_lshlrev_b32_e32 v62, 17, v60
	v_lshl_add_u32 v62, v55, 4, v62
	v_add_u32_e32 v62, s23, v62
	v_add_u32_e32 v62, 0x1000, v62
	v_mov_b32_e32 v63, 0
	v_lshl_add_u64 v[50:51], s[24:25], 0, v[62:63]
	s_lshl_b32 s18, s74, 13
	v_lshl_add_u32 v62, v60, 10, s18
	v_lshl_add_u64 v[52:53], s[20:21], 0, v[62:63]
	v_mov_b32_e32 v56, 0
	v_mov_b32_e32 v57, 0
	v_mov_b32_e32 v58, 0
	v_mov_b32_e32 v59, 0
	s_mov_b32 s19, 8
.Lbias_round:
	global_load_dwordx4 v[196:199], v[52:53], off
	global_load_dwordx4 v[200:203], v[52:53], off offset:16
	global_load_dwordx4 v[204:207], v[52:53], off offset:32
	global_load_dwordx4 v[208:211], v[52:53], off offset:48
	global_load_dwordx4 v[212:215], v[52:53], off offset:64
	global_load_dwordx4 v[216:219], v[52:53], off offset:80
	global_load_dwordx4 v[220:223], v[52:53], off offset:96
	global_load_dwordx4 v[224:227], v[52:53], off offset:112
	global_load_dwordx4 v[64:67], v[50:51], off offset:-4096
	global_load_dwordx4 v[68:71], v[50:51], off offset:-3584
	global_load_dwordx4 v[72:75], v[50:51], off offset:-3072
	global_load_dwordx4 v[76:79], v[50:51], off offset:-2560
	global_load_dwordx4 v[80:83], v[50:51], off offset:-2048
	global_load_dwordx4 v[84:87], v[50:51], off offset:-1536
	global_load_dwordx4 v[88:91], v[50:51], off offset:-1024
	global_load_dwordx4 v[92:95], v[50:51], off offset:-512
	global_load_dwordx4 v[96:99], v[50:51], off offset:0
	global_load_dwordx4 v[100:103], v[50:51], off offset:512
	global_load_dwordx4 v[104:107], v[50:51], off offset:1024
	global_load_dwordx4 v[108:111], v[50:51], off offset:1536
	global_load_dwordx4 v[112:115], v[50:51], off offset:2048
	global_load_dwordx4 v[116:119], v[50:51], off offset:2560
	global_load_dwordx4 v[120:123], v[50:51], off offset:3072
	global_load_dwordx4 v[124:127], v[50:51], off offset:3584
	v_add_co_u32_e32 v50, vcc, 0x2000, v50
	s_nop 1
	v_addc_co_u32_e32 v51, vcc, 0, v51, vcc
	global_load_dwordx4 v[128:131], v[50:51], off offset:-4096
	global_load_dwordx4 v[132:135], v[50:51], off offset:-3584
	global_load_dwordx4 v[138:141], v[50:51], off offset:-3072
	global_load_dwordx4 v[142:145], v[50:51], off offset:-2560
	global_load_dwordx4 v[146:149], v[50:51], off offset:-2048
	global_load_dwordx4 v[150:153], v[50:51], off offset:-1536
	global_load_dwordx4 v[154:157], v[50:51], off offset:-1024
	global_load_dwordx4 v[158:161], v[50:51], off offset:-512
	global_load_dwordx4 v[162:165], v[50:51], off offset:0
	global_load_dwordx4 v[166:169], v[50:51], off offset:512
	global_load_dwordx4 v[170:173], v[50:51], off offset:1024
	global_load_dwordx4 v[174:177], v[50:51], off offset:1536
	global_load_dwordx4 v[178:181], v[50:51], off offset:2048
	global_load_dwordx4 v[182:185], v[50:51], off offset:2560
	global_load_dwordx4 v[186:189], v[50:51], off offset:3072
	global_load_dwordx4 v[190:193], v[50:51], off offset:3584
	v_add_co_u32_e32 v50, vcc, 0x2000, v50
	s_nop 1
	v_addc_co_u32_e32 v51, vcc, 0, v51, vcc
	v_add_co_u32_e32 v52, vcc, 0x80, v52
	s_nop 1
	v_addc_co_u32_e32 v53, vcc, 0, v53, vcc
	s_waitcnt vmcnt(0)
	v_fmac_f32_e32 v56, v196, v64
	v_fmac_f32_e32 v57, v196, v65
	v_fmac_f32_e32 v58, v196, v66
	v_fmac_f32_e32 v59, v196, v67
	v_fmac_f32_e32 v56, v197, v68
	v_fmac_f32_e32 v57, v197, v69
	v_fmac_f32_e32 v58, v197, v70
	v_fmac_f32_e32 v59, v197, v71
	v_fmac_f32_e32 v56, v198, v72
	v_fmac_f32_e32 v57, v198, v73
	v_fmac_f32_e32 v58, v198, v74
	v_fmac_f32_e32 v59, v198, v75
	v_fmac_f32_e32 v56, v199, v76
	v_fmac_f32_e32 v57, v199, v77
	v_fmac_f32_e32 v58, v199, v78
	v_fmac_f32_e32 v59, v199, v79
	v_fmac_f32_e32 v56, v200, v80
	v_fmac_f32_e32 v57, v200, v81
	v_fmac_f32_e32 v58, v200, v82
	v_fmac_f32_e32 v59, v200, v83
	v_fmac_f32_e32 v56, v201, v84
	v_fmac_f32_e32 v57, v201, v85
	v_fmac_f32_e32 v58, v201, v86
	v_fmac_f32_e32 v59, v201, v87
	v_fmac_f32_e32 v56, v202, v88
	v_fmac_f32_e32 v57, v202, v89
	v_fmac_f32_e32 v58, v202, v90
	v_fmac_f32_e32 v59, v202, v91
	v_fmac_f32_e32 v56, v203, v92
	v_fmac_f32_e32 v57, v203, v93
	v_fmac_f32_e32 v58, v203, v94
	v_fmac_f32_e32 v59, v203, v95
	v_fmac_f32_e32 v56, v204, v96
	v_fmac_f32_e32 v57, v204, v97
	v_fmac_f32_e32 v58, v204, v98
	v_fmac_f32_e32 v59, v204, v99
	v_fmac_f32_e32 v56, v205, v100
	v_fmac_f32_e32 v57, v205, v101
	v_fmac_f32_e32 v58, v205, v102
	v_fmac_f32_e32 v59, v205, v103
	v_fmac_f32_e32 v56, v206, v104
	v_fmac_f32_e32 v57, v206, v105
	v_fmac_f32_e32 v58, v206, v106
	v_fmac_f32_e32 v59, v206, v107
	v_fmac_f32_e32 v56, v207, v108
	v_fmac_f32_e32 v57, v207, v109
	v_fmac_f32_e32 v58, v207, v110
	v_fmac_f32_e32 v59, v207, v111
	v_fmac_f32_e32 v56, v208, v112
	v_fmac_f32_e32 v57, v208, v113
	v_fmac_f32_e32 v58, v208, v114
	v_fmac_f32_e32 v59, v208, v115
	v_fmac_f32_e32 v56, v209, v116
	v_fmac_f32_e32 v57, v209, v117
	v_fmac_f32_e32 v58, v209, v118
	v_fmac_f32_e32 v59, v209, v119
	v_fmac_f32_e32 v56, v210, v120
	v_fmac_f32_e32 v57, v210, v121
	v_fmac_f32_e32 v58, v210, v122
	v_fmac_f32_e32 v59, v210, v123
	v_fmac_f32_e32 v56, v211, v124
	v_fmac_f32_e32 v57, v211, v125
	v_fmac_f32_e32 v58, v211, v126
	v_fmac_f32_e32 v59, v211, v127
	v_fmac_f32_e32 v56, v212, v128
	v_fmac_f32_e32 v57, v212, v129
	v_fmac_f32_e32 v58, v212, v130
	v_fmac_f32_e32 v59, v212, v131
	v_fmac_f32_e32 v56, v213, v132
	v_fmac_f32_e32 v57, v213, v133
	v_fmac_f32_e32 v58, v213, v134
	v_fmac_f32_e32 v59, v213, v135
	v_fmac_f32_e32 v56, v214, v138
	v_fmac_f32_e32 v57, v214, v139
	v_fmac_f32_e32 v58, v214, v140
	v_fmac_f32_e32 v59, v214, v141
	v_fmac_f32_e32 v56, v215, v142
	v_fmac_f32_e32 v57, v215, v143
	v_fmac_f32_e32 v58, v215, v144
	v_fmac_f32_e32 v59, v215, v145
	v_fmac_f32_e32 v56, v216, v146
	v_fmac_f32_e32 v57, v216, v147
	v_fmac_f32_e32 v58, v216, v148
	v_fmac_f32_e32 v59, v216, v149
	v_fmac_f32_e32 v56, v217, v150
	v_fmac_f32_e32 v57, v217, v151
	v_fmac_f32_e32 v58, v217, v152
	v_fmac_f32_e32 v59, v217, v153
	v_fmac_f32_e32 v56, v218, v154
	v_fmac_f32_e32 v57, v218, v155
	v_fmac_f32_e32 v58, v218, v156
	v_fmac_f32_e32 v59, v218, v157
	v_fmac_f32_e32 v56, v219, v158
	v_fmac_f32_e32 v57, v219, v159
	v_fmac_f32_e32 v58, v219, v160
	v_fmac_f32_e32 v59, v219, v161
	v_fmac_f32_e32 v56, v220, v162
	v_fmac_f32_e32 v57, v220, v163
	v_fmac_f32_e32 v58, v220, v164
	v_fmac_f32_e32 v59, v220, v165
	v_fmac_f32_e32 v56, v221, v166
	v_fmac_f32_e32 v57, v221, v167
	v_fmac_f32_e32 v58, v221, v168
	v_fmac_f32_e32 v59, v221, v169
	v_fmac_f32_e32 v56, v222, v170
	v_fmac_f32_e32 v57, v222, v171
	v_fmac_f32_e32 v58, v222, v172
	v_fmac_f32_e32 v59, v222, v173
	v_fmac_f32_e32 v56, v223, v174
	v_fmac_f32_e32 v57, v223, v175
	v_fmac_f32_e32 v58, v223, v176
	v_fmac_f32_e32 v59, v223, v177
	v_fmac_f32_e32 v56, v224, v178
	v_fmac_f32_e32 v57, v224, v179
	v_fmac_f32_e32 v58, v224, v180
	v_fmac_f32_e32 v59, v224, v181
	v_fmac_f32_e32 v56, v225, v182
	v_fmac_f32_e32 v57, v225, v183
	v_fmac_f32_e32 v58, v225, v184
	v_fmac_f32_e32 v59, v225, v185
	v_fmac_f32_e32 v56, v226, v186
	v_fmac_f32_e32 v57, v226, v187
	v_fmac_f32_e32 v58, v226, v188
	v_fmac_f32_e32 v59, v226, v189
	v_fmac_f32_e32 v56, v227, v190
	v_fmac_f32_e32 v57, v227, v191
	v_fmac_f32_e32 v58, v227, v192
	v_fmac_f32_e32 v59, v227, v193
	s_sub_i32 s19, s19, 1
	s_cmp_lg_u32 s19, 0
	s_cbranch_scc1 .Lbias_round
	v_lshlrev_b32_e32 v61, 2, v54
	v_xor_b32_e32 v62, 32, v61
	s_waitcnt lgkmcnt(0)
	ds_bpermute_b32 v64, v62, v56
	ds_bpermute_b32 v65, v62, v57
	ds_bpermute_b32 v66, v62, v58
	ds_bpermute_b32 v67, v62, v59
	s_waitcnt lgkmcnt(0)
	v_add_f32_e32 v56, v56, v64
	v_add_f32_e32 v57, v57, v65
	v_add_f32_e32 v58, v58, v66
	v_add_f32_e32 v59, v59, v67
	v_xor_b32_e32 v62, 64, v61
	s_waitcnt lgkmcnt(0)
	ds_bpermute_b32 v64, v62, v56
	ds_bpermute_b32 v65, v62, v57
	ds_bpermute_b32 v66, v62, v58
	ds_bpermute_b32 v67, v62, v59
	s_waitcnt lgkmcnt(0)
	v_add_f32_e32 v56, v56, v64
	v_add_f32_e32 v57, v57, v65
	v_add_f32_e32 v58, v58, v66
	v_add_f32_e32 v59, v59, v67
	v_xor_b32_e32 v62, 0x80, v61
	s_waitcnt lgkmcnt(0)
	ds_bpermute_b32 v64, v62, v56
	ds_bpermute_b32 v65, v62, v57
	ds_bpermute_b32 v66, v62, v58
	ds_bpermute_b32 v67, v62, v59
	s_waitcnt lgkmcnt(0)
	v_add_f32_e32 v56, v56, v64
	v_add_f32_e32 v57, v57, v65
	v_add_f32_e32 v58, v58, v66
	v_add_f32_e32 v59, v59, v67
	v_cmp_gt_u32_e32 vcc, 8, v54
	s_and_saveexec_b64 s[18:19], vcc
	s_lshl_b32 s20, s22, 7
	v_lshl_add_u32 v62, v55, 4, s20
	v_mov_b32_e32 v63, 0
	v_lshl_add_u64 v[62:63], s[14:15], 0, v[62:63]
	global_store_dwordx4 v[62:63], v[56:59], off
	s_or_b64 exec, exec, s[18:19]
	s_movk_i32 s6, 0x300
	s_mov_b64 s[18:19], 0
